# dilated attention: rebuild T5 bias tables only when the head changes between block-tasks
# baseline (speedup 1.0000x reference)
; #define LAS __attribute__((address_space(3)))
; __device__ __forceinline__ int otid() { int t = threadIdx.x; asm volatile("" : "+v"(t)); return t; }
; __device__ void ph_dilated_mfma(const Params& P, const bf16_t* __restrict__ proj, bf16_t* __restrict__ yout, unsigned char* lds_raw, float* __restrict__ Xall) {
;     const int tid = otid(); const int lane = tid & 63, wid = tid >> 6;
;     LAS float* tbl = (LAS float*)lds_raw; LAS unsigned char* wl = (LAS unsigned char*)lds_raw + 32768 + wid * 4608;
;     const float* rel_bias = P.in[17];
;     const int G = gridDim.x, bid = blockIdx.x, vb = (G % 8 == 0) ? (bid & 7) * (G >> 3) + (bid >> 3) : bid;
;     float* X = Xall + (size_t)bid * 512 * 68;
; #pragma unroll 1
;     for (int bt = vb; bt < 1024; bt += G) {
;         const int p = bt >> 3, chunk = bt & 7, b = p >> 4, h = p & 15;
;         __syncthreads();
;         LAS float* tbl16 = tbl; LAS float* tbl4 = tbl + 3328; LAS float* tblB = tbl + 6656;
;         for (int x = tid; x < 3073; x += NT) { const int rel = x - 1536, ar = rel < 0 ? -rel : rel; const float bv = rel_bias[t5_bucket(rel) * 16 + h] * 1.44269504088896341f;
;             tbl16[x + (x >> 4)] = ((rel & 15) == 0 && ar <= 1024) ? bv : -1e30f; tbl4[x + (x >> 4)] = ((rel & 3) == 0 && ar <= 256) ? bv : -1e30f; }
;         for (int x = tid; x < 256; x += NT) { const int rel = x - 96, ar = rel < 0 ? -rel : rel; tblB[x] = (ar <= 64) ? rel_bias[t5_bucket(rel) * 16 + h] * 1.44269504088896341f : -1e30f; }
;         __syncthreads();
.LBB0_577:
	s_andn2_b64 vcc, exec, s[6:7]
	s_cbranch_vccnz .LBB0_603
	v_mov_b32_e32 v113, v195
	s_and_b64 vcc, exec, s[38:39]
	s_cbranch_vccnz .LBB0_603
	v_ashrrev_i32_e32 v0, 6, v113
	s_movk_i32 s0, 0x1200
	v_mul_lo_u32 v1, v0, s0
	s_movk_i32 s0, 0xc01
	v_cmp_gt_i32_e64 s[0:1], s0, v113
	v_and_b32_e32 v2, 63, v113
	v_and_b32_e32 v151, 31, v113
	v_writelane_b32 v255, s0, 47
	v_bfe_u32 v156, v113, 3, 3
	v_add_u32_e32 v1, 0, v1
	v_writelane_b32 v255, s1, 48
	s_movk_i32 s0, 0x100
	v_cmp_gt_i32_e64 s[0:1], s0, v113
	v_lshlrev_b32_e32 v150, 1, v0
	v_bfe_u32 v3, v113, 5, 1
	v_writelane_b32 v255, s0, 45
	v_lshlrev_b32_e32 v0, 2, v2
	v_lshlrev_b32_e32 v152, 4, v151
	v_writelane_b32 v255, s1, 46
	v_lshlrev_b32_e32 v4, 4, v156
	s_movk_i32 s0, 0x240
	v_cmp_gt_u32_e64 s[42:43], 32, v2
	v_lshlrev_b32_e32 v2, 4, v113
	v_or_b32_e32 v157, 0xfffffc00, v4
	v_or_b32_e32 v158, 0xfffffc80, v4
	v_or_b32_e32 v159, 0xfffffd00, v4
	v_or_b32_e32 v160, 0xfffffd80, v4
	v_and_b32_e32 v4, 0x70, v152
	v_mad_u32_u24 v6, v3, s0, v1
	v_and_b32_e32 v2, 0x70, v2
	v_readlane_b32 s0, v254, 17
	v_lshlrev_b32_e32 v192, 3, v3
	v_add_u32_e32 v4, v1, v4
	v_add_u32_e32 v1, v1, v2
	v_readlane_b32 s1, v254, 18
	v_and_b32_e32 v2, 3, v113
	v_xor_b32_e32 v153, 0x80, v0
	v_lshlrev_b32_e32 v0, 3, v113
	v_lshlrev_b32_e32 v112, 2, v3
	v_lshl_add_u64 v[114:115], s[0:1], 0, v[192:193]
	v_cmp_eq_u32_e64 s[46:47], 0, v2
	v_readlane_b32 s0, v255, 23
	v_lshlrev_b32_e32 v2, 4, v3
	v_lshlrev_b32_e32 v3, 2, v151
	v_or_b32_e32 v154, 0xffffffc0, v151
	v_and_b32_e32 v0, 56, v0
	v_mul_u32_u24_e32 v5, 0x90, v156
	v_lshlrev_b32_e32 v7, 1, v151
	v_and_b32_e32 v8, 15, v113
	v_lshl_add_u32 v167, v113, 2, s0
	v_sub_u32_e32 v2, v2, v3
	v_readlane_b32 s0, v255, 24
	v_lshlrev_b32_e32 v155, 4, v154
	v_or_b32_e32 v161, 0xffffffc0, v156
	v_and_b32_e32 v162, 0xffffffc0, v113
	v_or_b32_e32 v163, 0xffffffc8, v156
	v_or_b32_e32 v164, 0xffffffd0, v156
	v_or_b32_e32 v165, 0xffffffd8, v156
	v_cmp_eq_u32_e64 s[44:45], 0, v8
	v_sub_u32_e32 v166, 0x600, v113
	v_sub_u32_e32 v168, 0x60, v113
	v_add_u32_e32 v169, s0, v2
	v_lshlrev_b32_e32 v116, 1, v192
	v_lshlrev_b32_e32 v118, 1, v0
	v_add_u32_e32 v170, v4, v5
	v_add_u32_e32 v171, v1, v5
	v_add_u32_e32 v172, v6, v7
	v_readlane_b32 s12, v255, 19
	v_readlane_b32 s17, v255, 18
	s_mov_b32 s101, -1
.LBB0_580:
	s_bfe_u32 s0, s17, 0x40003
	s_barrier
	s_mov_b64 s[6:7], exec
	s_mov_b32 s100, 1
	s_cmp_eq_u32 s0, s101
	s_cbranch_scc1 .LBB0_588
	s_mov_b32 s100, 0
	s_mov_b32 s101, s0
	v_readlane_b32 s10, v255, 47
	v_readlane_b32 s11, v255, 48
	s_and_b64 s[10:11], s[6:7], s[10:11]
	s_mov_b32 s18, 0x3f317217
	s_mov_b32 s19, 0x409b43d5
	s_mov_b64 exec, s[10:11]
	s_cbranch_execz .LBB0_583
	s_mov_b64 s[14:15], 0
	v_mov_b32_e32 v0, v166
	v_mov_b32_e32 v1, v113

; #define LAS __attribute__((address_space(3)))
; __device__ void ph_dilated_mfma(const Params& P, const bf16_t* __restrict__ proj, bf16_t* __restrict__ yout, unsigned char* lds_raw, float* __restrict__ Xall) {
;     ...
;         const int p = bt >> 3, chunk = bt & 7, b = p >> 4, h = p & 15;
;         __syncthreads();
;         LAS float* tbl16 = tbl; LAS float* tbl4 = tbl + 3328; LAS float* tblB = tbl + 6656;
;         for (int x = tid; x < 3073; x += NT) { const int rel = x - 1536, ar = rel < 0 ? -rel : rel; const float bv = rel_bias[t5_bucket(rel) * 16 + h] * 1.44269504088896341f;
;             tbl16[x + (x >> 4)] = ((rel & 15) == 0 && ar <= 1024) ? bv : -1e30f; tbl4[x + (x >> 4)] = ((rel & 3) == 0 && ar <= 256) ? bv : -1e30f; }
;         for (int x = tid; x < 256; x += NT) { const int rel = x - 96, ar = rel < 0 ? -rel : rel; tblB[x] = (ar <= 64) ? rel_bias[t5_bucket(rel) * 16 + h] * 1.44269504088896341f : -1e30f; }
;         __syncthreads();
; #pragma unroll 1
;         for (int rr = 0; rr < 2; ++rr) { const int res = wid * 2 + rr; DilPolA pol{chunk * 512 + res, res, tbl16, tbl4}; attn_wave_task<DilPolA, 1>(proj, b, h, pol, yout, lane, X, wl); }
.LBB0_588:
	s_or_b64 exec, exec, s[6:7]
	s_ashr_i32 s1, s17, 7
	s_lshl_b32 s6, s17, 9
	s_and_b32 s30, s6, 0xe00
	s_lshl_b32 s6, s1, 4
	s_or_b32 s6, s6, s0
	s_ashr_i32 s7, s6, 31
	s_lshl_b64 s[6:7], s[6:7], 19
	v_readlane_b32 s10, v252, 36
	v_readlane_b32 s11, v252, 37
	s_add_u32 s6, s10, s6
	s_addc_u32 s7, s11, s7
	v_mov_b32_e32 v117, v193
	v_lshl_add_u64 v[120:121], s[6:7], 0, v[116:117]
	s_mov_b64 s[10:11], 0x4000000
	v_mov_b32_e32 v119, v193
	v_lshl_add_u64 v[122:123], v[120:121], 0, s[10:11]
	v_lshl_add_u64 v[0:1], s[6:7], 0, v[118:119]
	s_mov_b64 s[10:11], 0x8000000
	v_lshl_add_u64 v[124:125], v[0:1], 0, s[10:11]
	s_mov_b32 s23, 0
	s_mov_b64 s[10:11], -1
	s_waitcnt lgkmcnt(0)
	s_cmp_eq_u32 s100, 1
	s_cbranch_scc1 .LBB0_590
	s_barrier
	s_branch .LBB0_590
